# leading-half epilogue-alignment barrier back at the epilogue entry in P3/P4/P6 (before the epilogue loads are issued), as in the baseline
# baseline (speedup 1.0000x reference)
; __device__ __forceinline__ unsigned cvt_pk_bf16(float lo, float hi) { const f32x2c_t v = {lo, hi}; const bf16x2c_t b = __builtin_convertvector(v, bf16x2c_t); return __builtin_bit_cast(unsigned, b); }
;     __device__ __forceinline__ void operator()(const f32x4 (&acc)[2][2][4][2], const Unit& u, int wr, int wc, int fr, int fq) const {
;     ...
;         const int row0 = u.pm * BM + wr * 64 + fr, col0 = u.pn * BM + wc * 32 + 8 * fq;
;         const float* xbase = (u.pm * BM < TP) ? xp : (xs - (size_t)TP * DM);
; #pragma unroll
;         for (int ai = 0; ai < 2; ++ai) {
;             f32x4 xv[4][2][2];
; #pragma unroll
;             for (int m = 0; m < 4; ++m)
; #pragma unroll
;                 for (int bj = 0; bj < 2; ++bj) { const size_t off = (size_t)(row0 + ai * HALF + m * 16) * DM + col0 + bj * HALF; xv[m][bj][0] = *(const f32x4*)(xbase + off); xv[m][bj][1] = *(const f32x4*)(xbase + off + 4); }
; #pragma unroll
;             for (int m = 0; m < 4; ++m) { const size_t r = (size_t)(row0 + ai * HALF + m * 16); float ss = 0.f;
; #pragma unroll
;                 for (int bj = 0; bj < 2; ++bj) { const size_t off = r * DM + col0 + bj * HALF;
;                     const f32x4 v0 = acc[ai][bj][m][0] * ascale + xv[m][bj][0], v1 = acc[ai][bj][m][1] * ascale + xv[m][bj][1];
;                     if (!WB) { *(f32x4*)(out + off) = v0; *(f32x4*)(out + off + 4) = v1; }
;                     if (WB) { u32x4 w; w.x = cvt_pk_bf16(v0[0], v0[1]); w.y = cvt_pk_bf16(v0[2], v0[3]); w.z = cvt_pk_bf16(v1[0], v1[1]); w.w = cvt_pk_bf16(v1[2], v1[3]); *(u32x4*)(xb + off) = w; }
;                     ss += (v0[0] * v0[0] + v0[1] * v0[1]) + (v0[2] * v0[2] + v0[3] * v0[3]) + (v1[0] * v1[0] + v1[1] * v1[1]) + (v1[2] * v1[2] + v1[3] * v1[3]); }
;                 ss += __shfl_xor(ss, 16); ss += __shfl_xor(ss, 32);
;                 if (fq == 0) ssq[r * 16 + u.pn * 4 + wc] = ss; }
;             asm volatile("" ::: "memory"); }
.LBB0_345:
	s_lshl_b32 s0, s52, 8
	v_and_b32_e32 v178, 63, v254
	s_add_i32 s0, s0, s64
	v_and_or_b32 v196, v178, 15, s0
	s_lshl_b32 s0, s50, 8
	s_or_b32 s0, s0, s65
	v_ashrrev_i32_e32 v207, 1, v178
	v_and_b32_e32 v207, -8, v207
	v_add_u32_e32 v207, s0, v207
	s_cmp_lt_i32 s52, 64
	s_cselect_b32 s0, s37, s62
	s_cselect_b32 s1, s36, s61
	v_mov_b32_e32 v252, s1
	v_mov_b32_e32 v253, s0
	v_mov_b32_e32 v224, v196
	v_ashrrev_i32_e32 v225, 31, v196
	v_mov_b32_e32 v226, v207
	v_ashrrev_i32_e32 v227, 31, v207
	v_lshl_add_u64 v[252:253], v[226:227], 2, v[252:253]
	v_lshlrev_b64 v[250:251], 12, v[224:225]
	v_lshl_add_u64 v[252:253], v[252:253], 0, v[250:251]
	s_lshl_b32 s0, s50, 4
	s_lshl_b32 s1, s63, 2
	s_add_u32 s0, s0, s1
	s_mov_b32 s1, 0
	v_lshlrev_b64 v[248:249], 6, v[224:225]
	v_lshl_add_u64 v[248:249], s[12:13], 0, v[248:249]
	v_lshl_add_u64 v[248:249], v[248:249], 0, s[0:1]
	v_lshlrev_b64 v[250:251], 11, v[224:225]
	v_lshl_add_u64 v[250:251], s[16:17], 0, v[250:251]
	v_lshl_add_u64 v[224:225], v[226:227], 1, v[250:251]
	v_mov_b64_e32 v[226:227], v[248:249]
	s_mov_b64 s[78:79], 0x10000
	s_mov_b64 s[80:81], 0x50000
	s_mov_b64 s[82:83], 0x8000
	s_mov_b64 s[84:85], 0x28000
	s_mov_b64 s[86:87], 0x400
	s_mov_b64 s[88:89], 0x1400
	global_load_dwordx4 v[128:131], v[252:253], off
	global_load_dwordx4 v[132:135], v[252:253], off offset:16
	global_load_dwordx4 v[136:139], v[252:253], off offset:512
	global_load_dwordx4 v[140:143], v[252:253], off offset:528
	v_lshl_add_u64 v[252:253], v[252:253], 0, s[78:79]
	global_load_dwordx4 v[144:147], v[252:253], off
	global_load_dwordx4 v[148:151], v[252:253], off offset:16
	global_load_dwordx4 v[152:155], v[252:253], off offset:512
	global_load_dwordx4 v[156:159], v[252:253], off offset:528
	v_lshl_add_u64 v[252:253], v[252:253], 0, s[78:79]
	global_load_dwordx4 v[160:163], v[252:253], off
	global_load_dwordx4 v[164:167], v[252:253], off offset:16
	global_load_dwordx4 v[168:171], v[252:253], off offset:512
	global_load_dwordx4 v[172:175], v[252:253], off offset:528
	v_lshl_add_u64 v[252:253], v[252:253], 0, s[78:79]
	global_load_dwordx4 v[180:183], v[252:253], off
	global_load_dwordx4 v[184:187], v[252:253], off offset:16
	global_load_dwordx4 v[188:191], v[252:253], off offset:512
	global_load_dwordx4 v[192:195], v[252:253], off offset:528
	v_lshl_add_u64 v[252:253], v[252:253], 0, s[80:81]
	global_load_dwordx4 v[208:211], v[252:253], off
	global_load_dwordx4 v[212:215], v[252:253], off offset:16
	global_load_dwordx4 v[216:219], v[252:253], off offset:512
	global_load_dwordx4 v[220:223], v[252:253], off offset:528
	v_lshl_add_u64 v[252:253], v[252:253], 0, s[78:79]
	global_load_dwordx4 v[236:239], v[252:253], off
	global_load_dwordx4 v[240:243], v[252:253], off offset:16
	global_load_dwordx4 v[244:247], v[252:253], off offset:512
	global_load_dwordx4 v[248:251], v[252:253], off offset:528
	v_lshl_add_u64 v[252:253], v[252:253], 0, s[78:79]
	v_and_b32_e32 v196, 64, v204
	v_add_u32_e32 v196, 64, v196
	v_xor_b32_e32 v205, 16, v204
	v_cmp_lt_i32_e32 vcc, v205, v196
	s_nop 1
	v_cndmask_b32_e32 v205, v204, v205, vcc
	v_lshlrev_b32_e32 v205, 2, v205
	v_xor_b32_e32 v206, 32, v204
	v_cmp_lt_i32_e32 vcc, v206, v196
	s_nop 1
	v_cndmask_b32_e32 v206, v204, v206, vcc
	v_lshlrev_b32_e32 v206, 2, v206
	v_cmp_gt_u32_e32 vcc, 16, v178
	s_waitcnt vmcnt(20)
	v_pk_fma_f32 v[116:117], v[116:117], s[40:41], v[128:129] op_sel_hi:[1,0,1]
	v_pk_fma_f32 v[118:119], v[118:119], s[40:41], v[130:131] op_sel_hi:[1,0,1]
	v_pk_fma_f32 v[112:113], v[112:113], s[40:41], v[132:133] op_sel_hi:[1,0,1]
	v_pk_fma_f32 v[114:115], v[114:115], s[40:41], v[134:135] op_sel_hi:[1,0,1]
	v_pk_fma_f32 v[124:125], v[124:125], s[40:41], v[136:137] op_sel_hi:[1,0,1]
	v_pk_fma_f32 v[126:127], v[126:127], s[40:41], v[138:139] op_sel_hi:[1,0,1]
	v_pk_fma_f32 v[120:121], v[120:121], s[40:41], v[140:141] op_sel_hi:[1,0,1]
	v_pk_fma_f32 v[122:123], v[122:123], s[40:41], v[142:143] op_sel_hi:[1,0,1]
	v_mul_f32_e32 v128, v117, v117
	v_mul_f32_e32 v129, v119, v119
	v_mul_f32_e32 v130, v113, v113
	v_mul_f32_e32 v131, v115, v115
	v_mul_f32_e32 v132, v125, v125
	v_mul_f32_e32 v133, v127, v127
	v_mul_f32_e32 v134, v121, v121
	v_mul_f32_e32 v135, v123, v123
	v_fmac_f32_e32 v128, v116, v116
	v_fmac_f32_e32 v129, v118, v118
	v_fmac_f32_e32 v130, v112, v112
	v_fmac_f32_e32 v131, v114, v114
	v_fmac_f32_e32 v132, v124, v124
	v_fmac_f32_e32 v133, v126, v126
	v_fmac_f32_e32 v134, v120, v120
	v_fmac_f32_e32 v135, v122, v122
	v_cvt_pk_bf16_f32 v136, v116, v117
	v_cvt_pk_bf16_f32 v137, v118, v119
	v_cvt_pk_bf16_f32 v138, v112, v113
	v_cvt_pk_bf16_f32 v139, v114, v115
	v_cvt_pk_bf16_f32 v140, v124, v125
	v_cvt_pk_bf16_f32 v141, v126, v127
	v_cvt_pk_bf16_f32 v142, v120, v121
	v_cvt_pk_bf16_f32 v143, v122, v123
	global_store_dwordx4 v[224:225], v[136:139], off
	global_store_dwordx4 v[224:225], v[140:143], off offset:256
	v_add_f32_e32 v128, v128, v129
	v_add_f32_e32 v130, v130, v131
	v_add_f32_e32 v132, v132, v133
	v_add_f32_e32 v134, v134, v135
	v_add_f32_e32 v128, v128, v130
	v_add_f32_e32 v132, v132, v134
	v_add_f32_e32 v128, v128, v132
	v_mov_b32_e32 v129, v128
	s_nop 1
	v_permlane16_swap_b32_e32 v128, v129
	s_nop 0
	v_add_f32_e32 v128, v128, v129
	v_mov_b32_e32 v129, v128
	s_nop 1
	v_permlane32_swap_b32_e32 v128, v129
	s_nop 0
	v_add_f32_e32 v128, v128, v129
	s_and_saveexec_b64 s[50:51], vcc
	global_store_dword v[226:227], v128, off
	s_or_b64 exec, exec, s[50:51]
	v_lshl_add_u64 v[224:225], v[224:225], 0, s[82:83]
	v_lshl_add_u64 v[226:227], v[226:227], 0, s[86:87]
	global_load_dwordx4 v[128:131], v[252:253], off
	global_load_dwordx4 v[132:135], v[252:253], off offset:16
	global_load_dwordx4 v[136:139], v[252:253], off offset:512
	global_load_dwordx4 v[140:143], v[252:253], off offset:528
	v_lshl_add_u64 v[252:253], v[252:253], 0, s[78:79]
	s_waitcnt vmcnt(23)
; __device__ __forceinline__ unsigned cvt_pk_bf16(float lo, float hi) { const f32x2c_t v = {lo, hi}; const bf16x2c_t b = __builtin_convertvector(v, bf16x2c_t); return __builtin_bit_cast(unsigned, b); }
;     __device__ __forceinline__ void operator()(const f32x4 (&acc)[2][2][4][2], const Unit& u, int wr, int wc, int fr, int fq) const {
;     ...
;             for (int m = 0; m < 4; ++m) { const size_t r = (size_t)(row0 + ai * HALF + m * 16); float ss = 0.f;
; #pragma unroll
;                 for (int bj = 0; bj < 2; ++bj) { const size_t off = r * DM + col0 + bj * HALF;
;                     const f32x4 v0 = acc[ai][bj][m][0] * ascale + xv[m][bj][0], v1 = acc[ai][bj][m][1] * ascale + xv[m][bj][1];
;                     if (!WB) { *(f32x4*)(out + off) = v0; *(f32x4*)(out + off + 4) = v1; }
;                     if (WB) { u32x4 w; w.x = cvt_pk_bf16(v0[0], v0[1]); w.y = cvt_pk_bf16(v0[2], v0[3]); w.z = cvt_pk_bf16(v1[0], v1[1]); w.w = cvt_pk_bf16(v1[2], v1[3]); *(u32x4*)(xb + off) = w; }
;                     ss += (v0[0] * v0[0] + v0[1] * v0[1]) + (v0[2] * v0[2] + v0[3] * v0[3]) + (v1[0] * v1[0] + v1[1] * v1[1]) + (v1[2] * v1[2] + v1[3] * v1[3]); }
;                 ss += __shfl_xor(ss, 16); ss += __shfl_xor(ss, 32);
;                 if (fq == 0) ssq[r * 16 + u.pn * 4 + wc] = ss; }
;             asm volatile("" ::: "memory"); }
	v_pk_fma_f32 v[108:109], v[108:109], s[40:41], v[144:145] op_sel_hi:[1,0,1]
	v_pk_fma_f32 v[110:111], v[110:111], s[40:41], v[146:147] op_sel_hi:[1,0,1]
	v_pk_fma_f32 v[100:101], v[100:101], s[40:41], v[148:149] op_sel_hi:[1,0,1]
	v_pk_fma_f32 v[102:103], v[102:103], s[40:41], v[150:151] op_sel_hi:[1,0,1]
	v_pk_fma_f32 v[104:105], v[104:105], s[40:41], v[152:153] op_sel_hi:[1,0,1]
	v_pk_fma_f32 v[106:107], v[106:107], s[40:41], v[154:155] op_sel_hi:[1,0,1]
	v_pk_fma_f32 v[96:97], v[96:97], s[40:41], v[156:157] op_sel_hi:[1,0,1]
	v_pk_fma_f32 v[98:99], v[98:99], s[40:41], v[158:159] op_sel_hi:[1,0,1]
	v_mul_f32_e32 v144, v109, v109
	v_mul_f32_e32 v145, v111, v111
	v_mul_f32_e32 v146, v101, v101
	v_mul_f32_e32 v147, v103, v103
	v_mul_f32_e32 v148, v105, v105
	v_mul_f32_e32 v149, v107, v107
	v_mul_f32_e32 v150, v97, v97
	v_mul_f32_e32 v151, v99, v99
	v_fmac_f32_e32 v144, v108, v108
	v_fmac_f32_e32 v145, v110, v110
	v_fmac_f32_e32 v146, v100, v100
	v_fmac_f32_e32 v147, v102, v102
	v_fmac_f32_e32 v148, v104, v104
	v_fmac_f32_e32 v149, v106, v106
	v_fmac_f32_e32 v150, v96, v96
	v_fmac_f32_e32 v151, v98, v98
	v_cvt_pk_bf16_f32 v152, v108, v109
	v_cvt_pk_bf16_f32 v153, v110, v111
	v_cvt_pk_bf16_f32 v154, v100, v101
	v_cvt_pk_bf16_f32 v155, v102, v103
	v_cvt_pk_bf16_f32 v156, v104, v105
	v_cvt_pk_bf16_f32 v157, v106, v107
	v_cvt_pk_bf16_f32 v158, v96, v97
	v_cvt_pk_bf16_f32 v159, v98, v99
	global_store_dwordx4 v[224:225], v[152:155], off
	global_store_dwordx4 v[224:225], v[156:159], off offset:256
	v_add_f32_e32 v144, v144, v145
	v_add_f32_e32 v146, v146, v147
	v_add_f32_e32 v148, v148, v149
	v_add_f32_e32 v150, v150, v151
	v_add_f32_e32 v144, v144, v146
	v_add_f32_e32 v148, v148, v150
	v_add_f32_e32 v144, v144, v148
	v_mov_b32_e32 v145, v144
	s_nop 1
	v_permlane16_swap_b32_e32 v144, v145
	s_nop 0
	v_add_f32_e32 v144, v144, v145
	v_mov_b32_e32 v145, v144
	s_nop 1
	v_permlane32_swap_b32_e32 v144, v145
	s_nop 0
	v_add_f32_e32 v144, v144, v145
	s_and_saveexec_b64 s[50:51], vcc
	global_store_dword v[226:227], v144, off
	s_or_b64 exec, exec, s[50:51]
	v_lshl_add_u64 v[224:225], v[224:225], 0, s[82:83]
	v_lshl_add_u64 v[226:227], v[226:227], 0, s[86:87]
	global_load_dwordx4 v[144:147], v[252:253], off
	global_load_dwordx4 v[148:151], v[252:253], off offset:16
	global_load_dwordx4 v[152:155], v[252:253], off offset:512
	global_load_dwordx4 v[156:159], v[252:253], off offset:528
	s_waitcnt vmcnt(26)
	v_pk_fma_f32 v[92:93], v[92:93], s[40:41], v[160:161] op_sel_hi:[1,0,1]
	v_pk_fma_f32 v[94:95], v[94:95], s[40:41], v[162:163] op_sel_hi:[1,0,1]
	v_pk_fma_f32 v[84:85], v[84:85], s[40:41], v[164:165] op_sel_hi:[1,0,1]
	v_pk_fma_f32 v[86:87], v[86:87], s[40:41], v[166:167] op_sel_hi:[1,0,1]
	v_pk_fma_f32 v[88:89], v[88:89], s[40:41], v[168:169] op_sel_hi:[1,0,1]
	v_pk_fma_f32 v[90:91], v[90:91], s[40:41], v[170:171] op_sel_hi:[1,0,1]
	v_pk_fma_f32 v[80:81], v[80:81], s[40:41], v[172:173] op_sel_hi:[1,0,1]
	v_pk_fma_f32 v[82:83], v[82:83], s[40:41], v[174:175] op_sel_hi:[1,0,1]
	v_mul_f32_e32 v160, v93, v93
	v_mul_f32_e32 v161, v95, v95
	v_mul_f32_e32 v162, v85, v85
	v_mul_f32_e32 v163, v87, v87
	v_mul_f32_e32 v164, v89, v89
	v_mul_f32_e32 v165, v91, v91
	v_mul_f32_e32 v166, v81, v81
	v_mul_f32_e32 v167, v83, v83
	v_fmac_f32_e32 v160, v92, v92
	v_fmac_f32_e32 v161, v94, v94
	v_fmac_f32_e32 v162, v84, v84
	v_fmac_f32_e32 v163, v86, v86
	v_fmac_f32_e32 v164, v88, v88
	v_fmac_f32_e32 v165, v90, v90
	v_fmac_f32_e32 v166, v80, v80
	v_fmac_f32_e32 v167, v82, v82
	v_cvt_pk_bf16_f32 v168, v92, v93
	v_cvt_pk_bf16_f32 v169, v94, v95
	v_cvt_pk_bf16_f32 v170, v84, v85
	v_cvt_pk_bf16_f32 v171, v86, v87
	v_cvt_pk_bf16_f32 v172, v88, v89
	v_cvt_pk_bf16_f32 v173, v90, v91
	v_cvt_pk_bf16_f32 v174, v80, v81
	v_cvt_pk_bf16_f32 v175, v82, v83
	global_store_dwordx4 v[224:225], v[168:171], off
	global_store_dwordx4 v[224:225], v[172:175], off offset:256
	v_add_f32_e32 v160, v160, v161
	v_add_f32_e32 v162, v162, v163
	v_add_f32_e32 v164, v164, v165
	v_add_f32_e32 v166, v166, v167
	v_add_f32_e32 v160, v160, v162
	v_add_f32_e32 v164, v164, v166
	v_add_f32_e32 v160, v160, v164
	v_mov_b32_e32 v161, v160
	s_nop 1
	v_permlane16_swap_b32_e32 v160, v161
	s_nop 0
	v_add_f32_e32 v160, v160, v161
	v_mov_b32_e32 v161, v160
	s_nop 1
	v_permlane32_swap_b32_e32 v160, v161
	s_nop 0
	v_add_f32_e32 v160, v160, v161
	s_and_saveexec_b64 s[50:51], vcc
	global_store_dword v[226:227], v160, off
	s_or_b64 exec, exec, s[50:51]
	v_lshl_add_u64 v[224:225], v[224:225], 0, s[82:83]
	v_lshl_add_u64 v[226:227], v[226:227], 0, s[86:87]
	s_waitcnt vmcnt(25)
	v_pk_fma_f32 v[76:77], v[76:77], s[40:41], v[180:181] op_sel_hi:[1,0,1]
	v_pk_fma_f32 v[78:79], v[78:79], s[40:41], v[182:183] op_sel_hi:[1,0,1]
	v_pk_fma_f32 v[68:69], v[68:69], s[40:41], v[184:185] op_sel_hi:[1,0,1]
	v_pk_fma_f32 v[70:71], v[70:71], s[40:41], v[186:187] op_sel_hi:[1,0,1]
	v_pk_fma_f32 v[72:73], v[72:73], s[40:41], v[188:189] op_sel_hi:[1,0,1]
	v_pk_fma_f32 v[74:75], v[74:75], s[40:41], v[190:191] op_sel_hi:[1,0,1]
	v_pk_fma_f32 v[64:65], v[64:65], s[40:41], v[192:193] op_sel_hi:[1,0,1]
	v_pk_fma_f32 v[66:67], v[66:67], s[40:41], v[194:195] op_sel_hi:[1,0,1]
	v_mul_f32_e32 v180, v77, v77
	v_mul_f32_e32 v181, v79, v79
	v_mul_f32_e32 v182, v69, v69
	v_mul_f32_e32 v183, v71, v71
	v_mul_f32_e32 v184, v73, v73
	v_mul_f32_e32 v185, v75, v75
	v_mul_f32_e32 v186, v65, v65
	v_mul_f32_e32 v187, v67, v67
	v_fmac_f32_e32 v180, v76, v76
	v_fmac_f32_e32 v181, v78, v78
	v_fmac_f32_e32 v182, v68, v68
	v_fmac_f32_e32 v183, v70, v70
	v_fmac_f32_e32 v184, v72, v72
	v_fmac_f32_e32 v185, v74, v74
	v_fmac_f32_e32 v186, v64, v64
	v_fmac_f32_e32 v187, v66, v66
	v_cvt_pk_bf16_f32 v188, v76, v77
	v_cvt_pk_bf16_f32 v189, v78, v79
	v_cvt_pk_bf16_f32 v190, v68, v69
	v_cvt_pk_bf16_f32 v191, v70, v71
	v_cvt_pk_bf16_f32 v192, v72, v73
	v_cvt_pk_bf16_f32 v193, v74, v75
	v_cvt_pk_bf16_f32 v194, v64, v65
	v_cvt_pk_bf16_f32 v195, v66, v67
	global_store_dwordx4 v[224:225], v[188:191], off
	global_store_dwordx4 v[224:225], v[192:195], off offset:256
	v_add_f32_e32 v180, v180, v181
	v_add_f32_e32 v182, v182, v183
	v_add_f32_e32 v184, v184, v185
	v_add_f32_e32 v186, v186, v187
	v_add_f32_e32 v180, v180, v182
	v_add_f32_e32 v184, v184, v186
	v_add_f32_e32 v180, v180, v184
	v_mov_b32_e32 v181, v180
	s_nop 1
	v_permlane16_swap_b32_e32 v180, v181
	s_nop 0
	v_add_f32_e32 v180, v180, v181
	v_mov_b32_e32 v181, v180
	s_nop 1
	v_permlane32_swap_b32_e32 v180, v181
	s_nop 0
	v_add_f32_e32 v180, v180, v181
	s_and_saveexec_b64 s[50:51], vcc
	global_store_dword v[226:227], v180, off
	s_or_b64 exec, exec, s[50:51]
	v_lshl_add_u64 v[224:225], v[224:225], 0, s[84:85]
	v_lshl_add_u64 v[226:227], v[226:227], 0, s[88:89]
	s_waitcnt vmcnt(24)
; __device__ __forceinline__ unsigned cvt_pk_bf16(float lo, float hi) { const f32x2c_t v = {lo, hi}; const bf16x2c_t b = __builtin_convertvector(v, bf16x2c_t); return __builtin_bit_cast(unsigned, b); }
;     __device__ __forceinline__ void operator()(const f32x4 (&acc)[2][2][4][2], const Unit& u, int wr, int wc, int fr, int fq) const {
;     ...
;             for (int m = 0; m < 4; ++m) { const size_t r = (size_t)(row0 + ai * HALF + m * 16); float ss = 0.f;
; #pragma unroll
;                 for (int bj = 0; bj < 2; ++bj) { const size_t off = r * DM + col0 + bj * HALF;
;                     const f32x4 v0 = acc[ai][bj][m][0] * ascale + xv[m][bj][0], v1 = acc[ai][bj][m][1] * ascale + xv[m][bj][1];
;                     if (!WB) { *(f32x4*)(out + off) = v0; *(f32x4*)(out + off + 4) = v1; }
;                     if (WB) { u32x4 w; w.x = cvt_pk_bf16(v0[0], v0[1]); w.y = cvt_pk_bf16(v0[2], v0[3]); w.z = cvt_pk_bf16(v1[0], v1[1]); w.w = cvt_pk_bf16(v1[2], v1[3]); *(u32x4*)(xb + off) = w; }
;                     ss += (v0[0] * v0[0] + v0[1] * v0[1]) + (v0[2] * v0[2] + v0[3] * v0[3]) + (v1[0] * v1[0] + v1[1] * v1[1]) + (v1[2] * v1[2] + v1[3] * v1[3]); }
;                 ss += __shfl_xor(ss, 16); ss += __shfl_xor(ss, 32);
;                 if (fq == 0) ssq[r * 16 + u.pn * 4 + wc] = ss; }
;             asm volatile("" ::: "memory"); }
	v_pk_fma_f32 v[52:53], v[52:53], s[40:41], v[208:209] op_sel_hi:[1,0,1]
	v_pk_fma_f32 v[54:55], v[54:55], s[40:41], v[210:211] op_sel_hi:[1,0,1]
	v_pk_fma_f32 v[48:49], v[48:49], s[40:41], v[212:213] op_sel_hi:[1,0,1]
	v_pk_fma_f32 v[50:51], v[50:51], s[40:41], v[214:215] op_sel_hi:[1,0,1]
	v_pk_fma_f32 v[60:61], v[60:61], s[40:41], v[216:217] op_sel_hi:[1,0,1]
	v_pk_fma_f32 v[62:63], v[62:63], s[40:41], v[218:219] op_sel_hi:[1,0,1]
	v_pk_fma_f32 v[56:57], v[56:57], s[40:41], v[220:221] op_sel_hi:[1,0,1]
	v_pk_fma_f32 v[58:59], v[58:59], s[40:41], v[222:223] op_sel_hi:[1,0,1]
	v_mul_f32_e32 v208, v53, v53
	v_mul_f32_e32 v209, v55, v55
	v_mul_f32_e32 v210, v49, v49
	v_mul_f32_e32 v211, v51, v51
	v_mul_f32_e32 v212, v61, v61
	v_mul_f32_e32 v213, v63, v63
	v_mul_f32_e32 v214, v57, v57
	v_mul_f32_e32 v215, v59, v59
	v_fmac_f32_e32 v208, v52, v52
	v_fmac_f32_e32 v209, v54, v54
	v_fmac_f32_e32 v210, v48, v48
	v_fmac_f32_e32 v211, v50, v50
	v_fmac_f32_e32 v212, v60, v60
	v_fmac_f32_e32 v213, v62, v62
	v_fmac_f32_e32 v214, v56, v56
	v_fmac_f32_e32 v215, v58, v58
	v_cvt_pk_bf16_f32 v216, v52, v53
	v_cvt_pk_bf16_f32 v217, v54, v55
	v_cvt_pk_bf16_f32 v218, v48, v49
	v_cvt_pk_bf16_f32 v219, v50, v51
	v_cvt_pk_bf16_f32 v220, v60, v61
	v_cvt_pk_bf16_f32 v221, v62, v63
	v_cvt_pk_bf16_f32 v222, v56, v57
	v_cvt_pk_bf16_f32 v223, v58, v59
	global_store_dwordx4 v[224:225], v[216:219], off
	global_store_dwordx4 v[224:225], v[220:223], off offset:256
	v_add_f32_e32 v208, v208, v209
	v_add_f32_e32 v210, v210, v211
	v_add_f32_e32 v212, v212, v213
	v_add_f32_e32 v214, v214, v215
	v_add_f32_e32 v208, v208, v210
	v_add_f32_e32 v212, v212, v214
	v_add_f32_e32 v208, v208, v212
	v_mov_b32_e32 v209, v208
	s_nop 1
	v_permlane16_swap_b32_e32 v208, v209
	s_nop 0
	v_add_f32_e32 v208, v208, v209
	v_mov_b32_e32 v209, v208
	s_nop 1
	v_permlane32_swap_b32_e32 v208, v209
	s_nop 0
	v_add_f32_e32 v208, v208, v209
	s_and_saveexec_b64 s[50:51], vcc
	global_store_dword v[226:227], v208, off
	s_or_b64 exec, exec, s[50:51]
	v_lshl_add_u64 v[224:225], v[224:225], 0, s[82:83]
	v_lshl_add_u64 v[226:227], v[226:227], 0, s[86:87]
	s_waitcnt vmcnt(23)
	v_pk_fma_f32 v[44:45], v[44:45], s[40:41], v[236:237] op_sel_hi:[1,0,1]
	v_pk_fma_f32 v[46:47], v[46:47], s[40:41], v[238:239] op_sel_hi:[1,0,1]
	v_pk_fma_f32 v[36:37], v[36:37], s[40:41], v[240:241] op_sel_hi:[1,0,1]
	v_pk_fma_f32 v[38:39], v[38:39], s[40:41], v[242:243] op_sel_hi:[1,0,1]
	v_pk_fma_f32 v[40:41], v[40:41], s[40:41], v[244:245] op_sel_hi:[1,0,1]
	v_pk_fma_f32 v[42:43], v[42:43], s[40:41], v[246:247] op_sel_hi:[1,0,1]
	v_pk_fma_f32 v[32:33], v[32:33], s[40:41], v[248:249] op_sel_hi:[1,0,1]
	v_pk_fma_f32 v[34:35], v[34:35], s[40:41], v[250:251] op_sel_hi:[1,0,1]
	v_mul_f32_e32 v236, v45, v45
	v_mul_f32_e32 v237, v47, v47
	v_mul_f32_e32 v238, v37, v37
	v_mul_f32_e32 v239, v39, v39
	v_mul_f32_e32 v240, v41, v41
	v_mul_f32_e32 v241, v43, v43
	v_mul_f32_e32 v242, v33, v33
	v_mul_f32_e32 v243, v35, v35
	v_fmac_f32_e32 v236, v44, v44
	v_fmac_f32_e32 v237, v46, v46
	v_fmac_f32_e32 v238, v36, v36
	v_fmac_f32_e32 v239, v38, v38
	v_fmac_f32_e32 v240, v40, v40
	v_fmac_f32_e32 v241, v42, v42
	v_fmac_f32_e32 v242, v32, v32
	v_fmac_f32_e32 v243, v34, v34
	v_cvt_pk_bf16_f32 v244, v44, v45
	v_cvt_pk_bf16_f32 v245, v46, v47
	v_cvt_pk_bf16_f32 v246, v36, v37
	v_cvt_pk_bf16_f32 v247, v38, v39
	v_cvt_pk_bf16_f32 v248, v40, v41
	v_cvt_pk_bf16_f32 v249, v42, v43
	v_cvt_pk_bf16_f32 v250, v32, v33
	v_cvt_pk_bf16_f32 v251, v34, v35
	global_store_dwordx4 v[224:225], v[244:247], off
	global_store_dwordx4 v[224:225], v[248:251], off offset:256
	v_add_f32_e32 v236, v236, v237
	v_add_f32_e32 v238, v238, v239
	v_add_f32_e32 v240, v240, v241
	v_add_f32_e32 v242, v242, v243
	v_add_f32_e32 v236, v236, v238
	v_add_f32_e32 v240, v240, v242
	v_add_f32_e32 v236, v236, v240
	v_mov_b32_e32 v237, v236
	s_nop 1
	v_permlane16_swap_b32_e32 v236, v237
	s_nop 0
	v_add_f32_e32 v236, v236, v237
	v_mov_b32_e32 v237, v236
	s_nop 1
	v_permlane32_swap_b32_e32 v236, v237
	s_nop 0
	v_add_f32_e32 v236, v236, v237
	s_and_saveexec_b64 s[50:51], vcc
	global_store_dword v[226:227], v236, off
	s_or_b64 exec, exec, s[50:51]
	v_lshl_add_u64 v[224:225], v[224:225], 0, s[82:83]
	v_lshl_add_u64 v[226:227], v[226:227], 0, s[86:87]
	s_waitcnt vmcnt(19)
	v_pk_fma_f32 v[28:29], v[28:29], s[40:41], v[128:129] op_sel_hi:[1,0,1]
	v_pk_fma_f32 v[30:31], v[30:31], s[40:41], v[130:131] op_sel_hi:[1,0,1]
	v_pk_fma_f32 v[20:21], v[20:21], s[40:41], v[132:133] op_sel_hi:[1,0,1]
	v_pk_fma_f32 v[22:23], v[22:23], s[40:41], v[134:135] op_sel_hi:[1,0,1]
	v_pk_fma_f32 v[24:25], v[24:25], s[40:41], v[136:137] op_sel_hi:[1,0,1]
	v_pk_fma_f32 v[26:27], v[26:27], s[40:41], v[138:139] op_sel_hi:[1,0,1]
	v_pk_fma_f32 v[16:17], v[16:17], s[40:41], v[140:141] op_sel_hi:[1,0,1]
	v_pk_fma_f32 v[18:19], v[18:19], s[40:41], v[142:143] op_sel_hi:[1,0,1]
	v_mul_f32_e32 v128, v29, v29
	v_mul_f32_e32 v129, v31, v31
	v_mul_f32_e32 v130, v21, v21
	v_mul_f32_e32 v131, v23, v23
	v_mul_f32_e32 v132, v25, v25
	v_mul_f32_e32 v133, v27, v27
	v_mul_f32_e32 v134, v17, v17
	v_mul_f32_e32 v135, v19, v19
	v_fmac_f32_e32 v128, v28, v28
	v_fmac_f32_e32 v129, v30, v30
	v_fmac_f32_e32 v130, v20, v20
	v_fmac_f32_e32 v131, v22, v22
	v_fmac_f32_e32 v132, v24, v24
	v_fmac_f32_e32 v133, v26, v26
	v_fmac_f32_e32 v134, v16, v16
	v_fmac_f32_e32 v135, v18, v18
	v_cvt_pk_bf16_f32 v136, v28, v29
	v_cvt_pk_bf16_f32 v137, v30, v31
	v_cvt_pk_bf16_f32 v138, v20, v21
	v_cvt_pk_bf16_f32 v139, v22, v23
	v_cvt_pk_bf16_f32 v140, v24, v25
	v_cvt_pk_bf16_f32 v141, v26, v27
	v_cvt_pk_bf16_f32 v142, v16, v17
	v_cvt_pk_bf16_f32 v143, v18, v19
	global_store_dwordx4 v[224:225], v[136:139], off
	global_store_dwordx4 v[224:225], v[140:143], off offset:256
	v_add_f32_e32 v128, v128, v129
	v_add_f32_e32 v130, v130, v131
	v_add_f32_e32 v132, v132, v133
	v_add_f32_e32 v134, v134, v135
	v_add_f32_e32 v128, v128, v130
	v_add_f32_e32 v132, v132, v134
	v_add_f32_e32 v128, v128, v132
	v_mov_b32_e32 v129, v128
	s_nop 1
	v_permlane16_swap_b32_e32 v128, v129
	s_nop 0
	v_add_f32_e32 v128, v128, v129
	v_mov_b32_e32 v129, v128
	s_nop 1
	v_permlane32_swap_b32_e32 v128, v129
	s_nop 0
	v_add_f32_e32 v128, v128, v129
	s_and_saveexec_b64 s[50:51], vcc
	global_store_dword v[226:227], v128, off
	s_or_b64 exec, exec, s[50:51]
	v_lshl_add_u64 v[224:225], v[224:225], 0, s[82:83]
	v_lshl_add_u64 v[226:227], v[226:227], 0, s[86:87]
	s_waitcnt vmcnt(15)
; __device__ __forceinline__ unsigned cvt_pk_bf16(float lo, float hi) { const f32x2c_t v = {lo, hi}; const bf16x2c_t b = __builtin_convertvector(v, bf16x2c_t); return __builtin_bit_cast(unsigned, b); }
; template <class Epi, class Sched, bool ALIGN_EPI = false, bool SP2 = false, bool FP8 = false>
; __device__ __forceinline__ void gemm_phase(PG8_LAS unsigned char* lds, const Gemm g, const Sched& S, const Epi& E) {
;     ...
;         if (!has_next) break;
; #pragma unroll
;         for (int a = 0; a < 2; ++a)
; #pragma unroll
;             for (int b = 0; b < 2; ++b)
; #pragma unroll
;                 for (int m = 0; m < 4; ++m)
; #pragma unroll
;                     for (int n = 0; n < 2; ++n) { acc[a][b][m][n] = (f32x4){0.f, 0.f, 0.f, 0.f}; if constexpr (FP8) asm volatile("" : "+v"(acc[a][b][m][n])); }
;         cur = nxt; cA = nA; cB = nB; ++ui;
;     __device__ __forceinline__ void operator()(const f32x4 (&acc)[2][2][4][2], const Unit& u, int wr, int wc, int fr, int fq) const {
;     ...
;                 for (int bj = 0; bj < 2; ++bj) { const size_t off = r * DM + col0 + bj * HALF;
;                     const f32x4 v0 = acc[ai][bj][m][0] * ascale + xv[m][bj][0], v1 = acc[ai][bj][m][1] * ascale + xv[m][bj][1];
;                     if (!WB) { *(f32x4*)(out + off) = v0; *(f32x4*)(out + off + 4) = v1; }
;                     if (WB) { u32x4 w; w.x = cvt_pk_bf16(v0[0], v0[1]); w.y = cvt_pk_bf16(v0[2], v0[3]); w.z = cvt_pk_bf16(v1[0], v1[1]); w.w = cvt_pk_bf16(v1[2], v1[3]); *(u32x4*)(xb + off) = w; }
;                     ss += (v0[0] * v0[0] + v0[1] * v0[1]) + (v0[2] * v0[2] + v0[3] * v0[3]) + (v1[0] * v1[0] + v1[1] * v1[1]) + (v1[2] * v1[2] + v1[3] * v1[3]); }
;                 ss += __shfl_xor(ss, 16); ss += __shfl_xor(ss, 32);
;                 if (fq == 0) ssq[r * 16 + u.pn * 4 + wc] = ss; }
	v_pk_fma_f32 v[12:13], v[12:13], s[40:41], v[144:145] op_sel_hi:[1,0,1]
	v_pk_fma_f32 v[14:15], v[14:15], s[40:41], v[146:147] op_sel_hi:[1,0,1]
	v_pk_fma_f32 v[4:5], v[4:5], s[40:41], v[148:149] op_sel_hi:[1,0,1]
	v_pk_fma_f32 v[6:7], v[6:7], s[40:41], v[150:151] op_sel_hi:[1,0,1]
	v_pk_fma_f32 v[8:9], v[8:9], s[40:41], v[152:153] op_sel_hi:[1,0,1]
	v_pk_fma_f32 v[10:11], v[10:11], s[40:41], v[154:155] op_sel_hi:[1,0,1]
	v_pk_fma_f32 v[0:1], v[0:1], s[40:41], v[156:157] op_sel_hi:[1,0,1]
	v_pk_fma_f32 v[2:3], v[2:3], s[40:41], v[158:159] op_sel_hi:[1,0,1]
	v_mul_f32_e32 v144, v13, v13
	v_mul_f32_e32 v145, v15, v15
	v_mul_f32_e32 v146, v5, v5
	v_mul_f32_e32 v147, v7, v7
	v_mul_f32_e32 v148, v9, v9
	v_mul_f32_e32 v149, v11, v11
	v_mul_f32_e32 v150, v1, v1
	v_mul_f32_e32 v151, v3, v3
	v_fmac_f32_e32 v144, v12, v12
	v_fmac_f32_e32 v145, v14, v14
	v_fmac_f32_e32 v146, v4, v4
	v_fmac_f32_e32 v147, v6, v6
	v_fmac_f32_e32 v148, v8, v8
	v_fmac_f32_e32 v149, v10, v10
	v_fmac_f32_e32 v150, v0, v0
	v_fmac_f32_e32 v151, v2, v2
	v_cvt_pk_bf16_f32 v152, v12, v13
	v_cvt_pk_bf16_f32 v153, v14, v15
	v_cvt_pk_bf16_f32 v154, v4, v5
	v_cvt_pk_bf16_f32 v155, v6, v7
	v_cvt_pk_bf16_f32 v156, v8, v9
	v_cvt_pk_bf16_f32 v157, v10, v11
	v_cvt_pk_bf16_f32 v158, v0, v1
	v_cvt_pk_bf16_f32 v159, v2, v3
	global_store_dwordx4 v[224:225], v[152:155], off
	global_store_dwordx4 v[224:225], v[156:159], off offset:256
	v_add_f32_e32 v144, v144, v145
	v_add_f32_e32 v146, v146, v147
	v_add_f32_e32 v148, v148, v149
	v_add_f32_e32 v150, v150, v151
	v_add_f32_e32 v144, v144, v146
	v_add_f32_e32 v148, v148, v150
	v_add_f32_e32 v144, v144, v148
	v_mov_b32_e32 v145, v144
	s_nop 1
	v_permlane16_swap_b32_e32 v144, v145
	s_nop 0
	v_add_f32_e32 v144, v144, v145
	v_mov_b32_e32 v145, v144
	s_nop 1
	v_permlane32_swap_b32_e32 v144, v145
	s_nop 0
	v_add_f32_e32 v144, v144, v145
	s_and_saveexec_b64 s[50:51], vcc
	global_store_dword v[226:227], v144, off
	s_or_b64 exec, exec, s[50:51]
	s_andn2_b64 vcc, exec, s[4:5]
	s_mov_b64 s[4:5], -1
	s_cbranch_vccnz .LBB0_338
	s_mov_b32 s9, s8
	s_mov_b32 s10, s8
	s_mov_b32 s11, s8
	s_waitcnt lgkmcnt(0)
	v_mov_b64_e32 v[0:1], s[8:9]
	v_mov_b64_e32 v[118:119], s[10:11]
	v_mov_b64_e32 v[114:115], s[10:11]
	v_mov_b64_e32 v[110:111], s[10:11]
	v_mov_b64_e32 v[102:103], s[10:11]
	v_mov_b64_e32 v[94:95], s[10:11]
	v_mov_b64_e32 v[86:87], s[10:11]
	v_mov_b64_e32 v[78:79], s[10:11]
	v_mov_b64_e32 v[70:71], s[10:11]
	v_mov_b64_e32 v[126:127], s[10:11]
	v_mov_b64_e32 v[122:123], s[10:11]
	v_mov_b64_e32 v[106:107], s[10:11]
	v_mov_b64_e32 v[98:99], s[10:11]
	v_mov_b64_e32 v[90:91], s[10:11]
	v_mov_b64_e32 v[82:83], s[10:11]
	v_mov_b64_e32 v[74:75], s[10:11]
	v_mov_b64_e32 v[66:67], s[10:11]
	v_mov_b64_e32 v[54:55], s[10:11]
	v_mov_b64_e32 v[50:51], s[10:11]
	v_mov_b64_e32 v[46:47], s[10:11]
	v_mov_b64_e32 v[38:39], s[10:11]
	v_mov_b64_e32 v[30:31], s[10:11]
	v_mov_b64_e32 v[22:23], s[10:11]
	v_mov_b64_e32 v[14:15], s[10:11]
	v_mov_b64_e32 v[4:5], s[8:9]
	v_mov_b64_e32 v[62:63], s[10:11]
	v_mov_b64_e32 v[58:59], s[10:11]
	v_mov_b64_e32 v[42:43], s[10:11]
	v_mov_b64_e32 v[34:35], s[10:11]
	v_mov_b64_e32 v[26:27], s[10:11]
	v_mov_b64_e32 v[18:19], s[10:11]
	v_mov_b64_e32 v[8:9], s[8:9]
	v_mov_b64_e32 v[2:3], s[10:11]
	v_mov_b64_e32 v[116:117], s[8:9]
	v_mov_b64_e32 v[112:113], s[8:9]
	v_mov_b64_e32 v[108:109], s[8:9]
	v_mov_b64_e32 v[100:101], s[8:9]
	v_mov_b64_e32 v[92:93], s[8:9]
	v_mov_b64_e32 v[84:85], s[8:9]
	v_mov_b64_e32 v[76:77], s[8:9]
	v_mov_b64_e32 v[68:69], s[8:9]
	v_mov_b64_e32 v[124:125], s[8:9]
	v_mov_b64_e32 v[120:121], s[8:9]
	v_mov_b64_e32 v[104:105], s[8:9]
	v_mov_b64_e32 v[96:97], s[8:9]
	v_mov_b64_e32 v[88:89], s[8:9]
	v_mov_b64_e32 v[80:81], s[8:9]
	v_mov_b64_e32 v[72:73], s[8:9]
	v_mov_b64_e32 v[64:65], s[8:9]
	v_mov_b64_e32 v[52:53], s[8:9]
	v_mov_b64_e32 v[48:49], s[8:9]
	v_mov_b64_e32 v[44:45], s[8:9]
	v_mov_b64_e32 v[36:37], s[8:9]
	v_mov_b64_e32 v[28:29], s[8:9]
	v_mov_b64_e32 v[20:21], s[8:9]
	v_mov_b64_e32 v[12:13], s[8:9]
	v_mov_b64_e32 v[6:7], s[10:11]
	v_mov_b64_e32 v[60:61], s[8:9]
	v_mov_b64_e32 v[56:57], s[8:9]
	v_mov_b64_e32 v[40:41], s[8:9]
	v_mov_b64_e32 v[32:33], s[8:9]
	v_mov_b64_e32 v[24:25], s[8:9]
	v_mov_b64_e32 v[16:17], s[8:9]
	v_mov_b64_e32 v[10:11], s[10:11]
	s_andn2_b64 vcc, exec, s[6:7]
	s_cbranch_vccnz .LBB0_337
	s_mov_b32 s100, 1
	s_branch .LBB0_337

;     __device__ __forceinline__ void operator()(f32x4 (&acc)[2][2][4][2], const Unit& u, int wr, int wc, int fr, int fq) const {
;         const int row0 = u.pm * BM + wr * 64 + fr, col0 = u.pn * BM + wc * 32 + 8 * fq;
; #pragma unroll
;         for (int ai = 0; ai < 2; ++ai) {
;             u32x4 xv[4][2];
; #pragma unroll
;             for (int m = 0; m < 4; ++m)
; #pragma unroll
;                 for (int bj = 0; bj < 2; ++bj) { const size_t off = (size_t)(row0 + ai * HALF + m * 16) * DM + col0 + bj * HALF; xv[m][bj] = *(const u32x4*)(xb + off); }
; #pragma unroll
;             for (int m = 0; m < 4; ++m) { const size_t r = (size_t)(row0 + ai * HALF + m * 16); float ss = 0.f;
; #pragma unroll
;                 for (int bj = 0; bj < 2; ++bj) { const u32x4 xw = xv[m][bj];
;                     const f32x4 x0 = {bf_lo(xw.x), bf_hi(xw.x), bf_lo(xw.y), bf_hi(xw.y)}, x1 = {bf_lo(xw.z), bf_hi(xw.z), bf_lo(xw.w), bf_hi(xw.w)};
;                     const f32x4 v0 = acc[ai][bj][m][0] + x0, v1 = acc[ai][bj][m][1] + x1; acc[ai][bj][m][0] = v0; acc[ai][bj][m][1] = v1;
;                     ss += (v0[0] * v0[0] + v0[1] * v0[1]) + (v0[2] * v0[2] + v0[3] * v0[3]) + (v1[0] * v1[0] + v1[1] * v1[1]) + (v1[2] * v1[2] + v1[3] * v1[3]); }
;                 ss += __shfl_xor(ss, 16); ss += __shfl_xor(ss, 32);
;                 if (fq == 0) __hip_atomic_store(ssq + r * 16 + u.pn * 4 + wc, ss, __ATOMIC_RELAXED, __HIP_MEMORY_SCOPE_AGENT); }
.LBB0_430:
	v_lshl_add_u32 v176, s38, 8, v198
	v_lshl_or_b32 v178, s6, 8, v200
	v_ashrrev_i32_e32 v179, 31, v178
	v_ashrrev_i32_e32 v177, 31, v176
	v_lshl_add_u64 v[196:197], v[178:179], 1, s[16:17]
	v_lshlrev_b64 v[128:129], 11, v[176:177]
	v_lshl_add_u64 v[128:129], v[196:197], 0, v[128:129]
	global_load_dwordx4 v[180:183], v[128:129], off
	global_load_dwordx4 v[184:187], v[128:129], off offset:256
	v_or_b32_e32 v174, 16, v176
	v_or_b32_e32 v172, 32, v176
	v_or_b32_e32 v170, 48, v176
	v_ashrrev_i32_e32 v175, 31, v174
	v_ashrrev_i32_e32 v173, 31, v172
	v_ashrrev_i32_e32 v171, 31, v170
	v_lshlrev_b64 v[128:129], 11, v[174:175]
	v_lshlrev_b64 v[130:131], 11, v[172:173]
	v_lshlrev_b64 v[132:133], 11, v[170:171]
	v_lshl_add_u64 v[128:129], v[196:197], 0, v[128:129]
	v_lshl_add_u64 v[130:131], v[196:197], 0, v[130:131]
	v_lshl_add_u64 v[188:189], v[196:197], 0, v[132:133]
	global_load_dwordx4 v[148:151], v[128:129], off
	global_load_dwordx4 v[144:147], v[128:129], off offset:256
	global_load_dwordx4 v[140:143], v[130:131], off
	global_load_dwordx4 v[136:139], v[130:131], off offset:256
	global_load_dwordx4 v[132:135], v[188:189], off
	s_nop 0
	global_load_dwordx4 v[128:131], v[188:189], off offset:256
	v_lshlrev_b64 v[254:255], 11, v[176:177]
	v_lshl_add_u64 v[254:255], v[196:197], 0, v[254:255]
	s_mov_b64 s[60:61], 0x40000
	v_lshl_add_u64 v[254:255], v[254:255], 0, s[60:61]
	global_load_dwordx4 v[222:225], v[254:255], off
	global_load_dwordx4 v[226:229], v[254:255], off offset:256
	s_mov_b64 s[60:61], 0x8000
	v_lshl_add_u64 v[254:255], v[254:255], 0, s[60:61]
	global_load_dwordx4 v[230:233], v[254:255], off
	global_load_dwordx4 v[234:237], v[254:255], off offset:256
	v_lshl_add_u64 v[254:255], v[254:255], 0, s[60:61]
	global_load_dwordx4 v[238:241], v[254:255], off
	global_load_dwordx4 v[242:245], v[254:255], off offset:256
	v_lshl_add_u64 v[254:255], v[254:255], 0, s[60:61]
	global_load_dwordx4 v[246:249], v[254:255], off
	global_load_dwordx4 v[250:253], v[254:255], off offset:256
	v_and_b32_e32 v189, 64, v204
	v_xor_b32_e32 v188, 16, v204
	v_add_u32_e32 v207, 64, v189
	v_cmp_lt_i32_e32 vcc, v188, v207
	s_lshl_b32 s40, s6, 2
	s_ashr_i32 s41, s40, 31
	v_cndmask_b32_e32 v188, v204, v188, vcc
	v_lshlrev_b32_e32 v206, 2, v188
	s_waitcnt vmcnt(8)
	v_lshlrev_b32_e32 v188, 16, v180
	v_and_b32_e32 v189, 0xffff0000, v180
	v_lshlrev_b32_e32 v180, 16, v181
	v_and_b32_e32 v181, 0xffff0000, v181
	v_lshlrev_b32_e32 v192, 16, v184
	v_and_b32_e32 v193, 0xffff0000, v184
	v_lshlrev_b32_e32 v184, 16, v185
	v_and_b32_e32 v185, 0xffff0000, v185
	v_lshlrev_b32_e32 v190, 16, v182
	v_and_b32_e32 v191, 0xffff0000, v182
	v_lshlrev_b32_e32 v194, 16, v186
	v_and_b32_e32 v195, 0xffff0000, v186
	v_pk_add_f32 v[126:127], v[126:127], v[180:181]
	v_pk_add_f32 v[124:125], v[124:125], v[188:189]
	v_pk_add_f32 v[118:119], v[118:119], v[184:185]
	v_pk_add_f32 v[116:117], v[116:117], v[192:193]
	v_lshlrev_b32_e32 v182, 16, v183
	v_and_b32_e32 v183, 0xffff0000, v183
	v_lshlrev_b32_e32 v186, 16, v187
	v_and_b32_e32 v187, 0xffff0000, v187
	v_pk_add_f32 v[120:121], v[120:121], v[190:191]
	v_pk_add_f32 v[112:113], v[112:113], v[194:195]
	v_mul_f32_e32 v180, v125, v125
	v_mul_f32_e32 v181, v127, v127
	v_mul_f32_e32 v184, v117, v117
	v_mul_f32_e32 v185, v119, v119
	v_pk_add_f32 v[122:123], v[122:123], v[182:183]
	v_pk_add_f32 v[114:115], v[114:115], v[186:187]
	v_mul_f32_e32 v182, v121, v121
	v_mul_f32_e32 v186, v113, v113
	v_fmac_f32_e32 v180, v124, v124
	v_fmac_f32_e32 v181, v126, v126
	v_fmac_f32_e32 v184, v116, v116
	v_fmac_f32_e32 v185, v118, v118
	v_mul_f32_e32 v183, v123, v123
	v_mul_f32_e32 v187, v115, v115
	v_fmac_f32_e32 v182, v120, v120
	v_fmac_f32_e32 v186, v112, v112
	v_add_f32_e32 v180, v180, v181
	v_add_f32_e32 v181, v184, v185
	v_fmac_f32_e32 v183, v122, v122
	v_fmac_f32_e32 v187, v114, v114
	v_add_f32_e32 v180, v182, v180
	v_add_f32_e32 v181, v186, v181
	v_add_f32_e32 v180, v183, v180
	v_add_f32_e32 v181, v187, v181
	v_add_f32_e32 v180, v180, v181
	v_mov_b32_e32 v181, v180
	s_nop 1
	v_permlane16_swap_b32_e32 v180, v181
	s_nop 0
	v_xor_b32_e32 v182, 32, v204
	v_cmp_lt_i32_e32 vcc, v182, v207
	v_lshlrev_b64 v[188:189], 6, v[176:177]
	s_waitcnt lgkmcnt(0)
	v_add_f32_e32 v180, v180, v181
	v_cndmask_b32_e32 v182, v204, v182, vcc
	v_lshlrev_b32_e32 v207, 2, v182
	v_mov_b32_e32 v181, v180
	s_nop 1
	v_permlane32_swap_b32_e32 v180, v181
	s_nop 0
	s_and_saveexec_b64 s[42:43], s[0:1]
	s_cbranch_execz .LBB0_432
	s_waitcnt lgkmcnt(0)
	v_add_f32_e32 v182, v180, v181
	v_lshl_add_u64 v[180:181], s[10:11], 0, v[188:189]
	v_lshl_add_u64 v[180:181], s[40:41], 2, v[180:181]
	s_lshl_b32 s6, s53, 2
	v_lshl_add_u64 v[180:181], v[180:181], 0, s[6:7]
	global_store_dword v[180:181], v182, off sc1
